# mix_conv_first: mixer work queue deals the pooling/conv blocks before the attention heads (dealing-order change only)
# baseline (speedup 1.0000x reference)
; #define ws (arg_ws())
; #define x (arg_in(0))
;     const int tid = launder_v((int)threadIdx.x), lane = tid & 63, r32 = lane & 31, hi = lane >> 5; const int wid = __builtin_amdgcn_readfirstlane(tid >> 6);
;     const int grp = wid >> 2;
;     const long rowbase = (long)b * SEQ; const int q0 = qb * QB;
;     const float sl0 = __builtin_amdgcn_exp2f(-(float)(h + 1)) * LOG2E;
;     const float s1 = bfr(sl0), s2 = bfr(sl0 - s1), s3 = bfr(sl0 - s1 - s2); const float sl = s1 + s2 + s3;
;     const bf16_t* Qw = proj + (rowbase + q0 + wid * 32) * INW + O_Q + h * 64;
;     const bf16_t* Kh = proj + rowbase * INW + O_K + h * 64; const bf16_t* Vh = proj + rowbase * INW + O_V + h * 64;
;     const unsigned lds0 = (unsigned)(uintptr_t)shm;
;     float* wsf = (float*)(shm + LDS_WS) + wid * 128;
;     const bf16_t* ksrc = Kh + (long)(16 * (wid & 3) + (lane >> 2)) * INW + (wid >> 2) * 32 + (((lane & 3) ^ ((lane >> 4) & 3))) * 8;
;     const bf16_t* vsrc = Vh + (long)(16 * (wid & 3) + (lane >> 2)) * INW + (wid >> 2) * 32 + (lane & 3) * 8;
;     const unsigned kdst = lds0 + LDS_K + wid * 1024, vdst = lds0 + LDS_V + wid * 1024;
;     const int d0t = 4 * qb;
;     int nR = NT - d0t, NTe = NT;
;     const int td = d0t + (wid >> 1);
;     ...
;     bf16x8 qr[4];
; #pragma unroll
;     for (int d0 = 0; d0 < 4; ++d0) qr[d0] = *reinterpret_cast<const bf16x8*>(&Qw[(long)r32 * INW + d0 * 16 + hi * 8]);
;     float ka2 = 0.f, kb2 = 0.f;
;     if (SKIP_T > 0) { const unsigned* knp = kn2 + ((b * 8 + h) * 2) * 64;
; __global__ void __launch_bounds__(NTHR, 2) mk_fwd(Args a) {
;     ...
;                     if (useq) { idx = (int)qw[it & 1]; if (idx >= 160) break; bsel = xg; if (tid == 0) nxt = __hip_atomic_fetch_add(qcnt, 1u, __ATOMIC_RELAXED, __HIP_MEMORY_SCOPE_AGENT); }
;                     else { if (sidx >= BATCH * 160) break; bsel = sidx / 160; idx = sidx % 160; sidx += G; }
;                     const int cls = idx >> 4, e = idx & 15;
;                     if (cls >= 8) {
;                         const int r = bsel * 32 + (idx - 128);
;                         poolconv_rows(proj + (size_t)bsel * BPAD, mix, (const bf16_t*)(ws + WS_WPT) + (size_t)l * 4 * 4096, arg_in(12) + l * 256, arg_in(13) + l * 768, r * 128, ldsl, launder_v(tid));
;                     } else {
;                         const int hsel = 7 - cls;
;                         const int qb = (e & 1) ? 8 + (e >> 1) : 7 - (e >> 1);
.LBB0_309:
	s_add_i32 s15, s16, 0x80
	s_sub_i32 s16, s16, 32
	s_cmp_lt_i32 s16, 0
	s_cselect_b32 s16, s15, s16
	s_ashr_i32 s15, s16, 4
	s_cmp_lt_i32 s15, 8
	s_mov_b64 s[36:37], -1
	s_cbranch_scc0 .LBB0_373
	s_bfe_u32 s17, s16, 0x30001
	s_sub_i32 s30, 7, s15
	s_and_b32 s14, s16, 1
	s_or_b32 s18, s17, 8
	s_xor_b32 s17, s17, 7
	s_cmp_eq_u32 s14, 0
	s_cselect_b32 s14, s17, s18
	s_movk_i32 s17, 0xa0
	s_ashr_i32 s19, s17, 31
	s_add_u32 s18, s0, s17
	s_addc_u32 s19, s1, s19
	s_load_dwordx2 s[18:19], s[18:19], 0x0
	s_ashr_i32 s45, s44, 31
	s_lshl_b64 s[20:21], s[44:45], 21
	v_mov_b32_e32 v168, v212
	s_waitcnt lgkmcnt(0)
	s_add_u32 s17, s18, s20
	s_addc_u32 s18, s19, s21
	s_add_u32 s20, s17, 0xb200000
	s_movk_i32 s17, 0xa0
	s_addc_u32 s28, s18, 0
	s_ashr_i32 s19, s17, 31
	s_add_u32 s18, s0, s17
	s_addc_u32 s19, s1, s19
	s_movk_i32 s17, 0x50
	s_load_dwordx2 s[48:49], s[18:19], 0x0
	s_ashr_i32 s19, s17, 31
	s_add_u32 s18, s0, s17
	s_addc_u32 s19, s1, s19
	s_load_dwordx2 s[66:67], s[18:19], 0x0
	s_lshl_b64 s[22:23], s[44:45], 12
	v_readfirstlane_b32 s17, v168
	s_ashr_i32 s25, s17, 6
	s_lshl_b32 s21, s14, 8
	s_or_b32 s18, s22, s21
	s_lshl_b32 s22, s25, 5
	s_lshl_b32 s70, s30, 6
	s_ashr_i32 s19, s17, 8
	s_ashr_i32 s26, s22, 31
	s_add_u32 s50, s18, s22
	s_addc_u32 s51, s23, s26
	s_mul_i32 s18, s51, 0x1400
	s_mul_hi_u32 s23, s50, 0x1400
	s_add_i32 s23, s23, s18
	s_mul_i32 s18, s50, 0x1400
	s_add_u32 s18, s20, s18
	s_addc_u32 s23, s28, s23
	s_lshl_b64 s[72:73], s[70:71], 1
	s_add_u32 s26, s18, s72
	s_addc_u32 s27, s23, s73
	s_mul_i32 s23, s44, 0x1400000
	s_mul_hi_i32 s18, s44, 0x1400000
	s_add_u32 s20, s20, s23
	s_addc_u32 s18, s28, s18
	s_add_u32 s38, s20, s72
	s_addc_u32 s39, s18, s73
	s_lshl_b32 s18, s25, 4
	v_bfe_u32 v0, v168, 2, 4
	v_and_or_b32 v0, s18, 48, v0
	v_mul_u32_u24_e32 v0, 0xa00, v0
	v_and_b32_e32 v170, 31, v168
	v_bfe_u32 v169, v168, 5, 1
	s_lshl_b32 s28, s19, 5
	v_lshlrev_b32_e32 v128, 1, v0
	s_ashr_i32 s29, s28, 31
	v_and_b32_e32 v68, 3, v168
	v_lshl_add_u64 v[16:17], s[38:39], 0, v[128:129]
	v_mul_u32_u24_e32 v0, 0xa00, v170
	v_lshlrev_b32_e32 v18, 4, v169
	s_lshl_b32 s20, s25, 9
	s_lshl_b32 s23, s25, 10
	v_lshl_or_b32 v12, v0, 1, v18
	v_lshl_add_u64 v[16:17], s[28:29], 1, v[16:17]
	v_lshlrev_b32_e32 v128, 4, v68
	s_cmp_lg_u32 0, -1
	global_load_dwordx4 v[0:3], v12, s[26:27]
	global_load_dwordx4 v[4:7], v12, s[26:27] offset:32
	global_load_dwordx4 v[8:11], v12, s[26:27] offset:64
	s_nop 0
	global_load_dwordx4 v[12:15], v12, s[26:27] offset:96
	v_lshl_add_u64 v[20:21], v[16:17], 0, v[128:129]
	s_mov_b64 s[26:27], 0x800
	s_cselect_b32 s18, 0, 0
	v_lshl_add_u64 v[146:147], v[20:21], 0, s[26:27]
	s_lshl_b32 s26, s30, 7
	s_lshl_b32 s27, s44, 10
	s_add_i32 s26, s26, s27
	s_add_i32 s45, s23, s18
	s_ashr_i32 s27, s26, 31
	s_add_i32 s18, s45, 0x8000
	s_lshl_b64 s[26:27], s[26:27], 2
	s_add_u32 s26, s85, s26
	v_and_b32_e32 v167, 63, v168
	v_bfe_u32 v93, v168, 4, 2
	s_addc_u32 s27, s94, s27
	s_add_i32 s22, s22, s21
	v_bitop3_b32 v22, v93, v168, 3 bitop3:0x78
	v_lshlrev_b32_e32 v19, 2, v167
	v_or_b32_e32 v171, s22, v170
	v_mov_b64_e32 v[20:21], s[38:39]
	global_load_dword v67, v19, s[26:27] sc1
	global_load_dword v66, v19, s[26:27] offset:256 sc1
	v_mad_i64_i32 v[20:21], s[26:27], v171, s6, v[20:21]
	v_lshlrev_b32_e32 v128, 4, v22
	v_lshl_add_u64 v[16:17], v[16:17], 0, v[128:129]
	s_mov_b64 s[26:27], 0x400
	v_mov_b32_e32 v19, v129
	v_lshl_add_u64 v[148:149], v[16:17], 0, s[26:27]
	v_mov_b32_e32 v16, 0xa0000
	v_lshl_add_u64 v[18:19], v[20:21], 0, v[18:19]
	v_mul_u32_u24_e32 v16, s14, v16
	v_lshlrev_b32_e32 v128, 1, v16
	global_load_dwordx4 v[24:27], v[18:19], off offset:1024
	global_load_dwordx4 v[28:31], v[18:19], off offset:1056
	global_load_dwordx4 v[32:35], v[18:19], off offset:1088
	s_nop 0
	global_load_dwordx4 v[16:19], v[18:19], off offset:1120
	v_lshl_add_u64 v[20:21], v[148:149], 0, v[128:129]
	s_mov_b32 s22, m0
	s_mov_b32 m0, s45
	s_nop 0
	global_load_lds_dwordx4 v[20:21], off
	s_mov_b32 m0, s22
	s_mov_b64 s[28:29], 0x50000
	v_lshl_add_u64 v[22:23], v[146:147], 0, v[128:129]
	s_mov_b32 s22, m0
	s_mov_b32 m0, s18
	s_nop 0
	global_load_lds_dwordx4 v[22:23], off
	s_mov_b32 m0, s22
	v_lshl_add_u64 v[36:37], v[20:21], 0, s[28:29]
	s_add_i32 s22, s45, 0x2000
	s_mov_b32 s26, m0
	s_mov_b32 m0, s22
	s_nop 0
	global_load_lds_dwordx4 v[36:37], off
	s_mov_b32 m0, s26
	v_lshl_add_u64 v[36:37], v[22:23], 0, s[28:29]
	s_add_i32 s22, s45, 0xa000
	s_mov_b32 s26, m0
	s_mov_b32 m0, s22
	s_nop 0
	global_load_lds_dwordx4 v[36:37], off
	s_mov_b32 m0, s26
	s_add_i32 s20, s20, 0
	s_add_i32 s20, s20, 0x10000
	v_cmp_eq_u32_e32 vcc, 0, v167
	s_waitcnt vmcnt(9)
	v_lshlrev_b32_e32 v37, 16, v0
	s_waitcnt vmcnt(3)
	v_lshlrev_b32_e32 v36, 16, v24
	v_fma_f32 v69, v37, v36, 0
	v_and_b32_e32 v36, 0xffff0000, v0
	v_and_b32_e32 v24, 0xffff0000, v24
	v_mul_f32_e32 v38, v36, v36
	v_fmac_f32_e32 v38, v37, v37
	v_fmac_f32_e32 v69, v36, v24
	v_lshlrev_b32_e32 v24, 16, v25
	v_lshlrev_b32_e32 v36, 16, v1
	v_fmac_f32_e32 v38, v36, v36
	v_fmac_f32_e32 v69, v36, v24
	v_and_b32_e32 v24, 0xffff0000, v25
	v_and_b32_e32 v25, 0xffff0000, v1
	v_fmac_f32_e32 v38, v25, v25
	v_fmac_f32_e32 v69, v25, v24
	v_lshlrev_b32_e32 v24, 16, v26
	v_lshlrev_b32_e32 v25, 16, v2
	v_fmac_f32_e32 v38, v25, v25
	v_fmac_f32_e32 v69, v25, v24
	v_and_b32_e32 v24, 0xffff0000, v26
	v_and_b32_e32 v25, 0xffff0000, v2
	v_fmac_f32_e32 v38, v25, v25
	v_fmac_f32_e32 v69, v25, v24
	v_lshlrev_b32_e32 v24, 16, v27
	v_lshlrev_b32_e32 v25, 16, v3
	v_fmac_f32_e32 v38, v25, v25
	v_fmac_f32_e32 v69, v25, v24
	v_and_b32_e32 v24, 0xffff0000, v27
	v_and_b32_e32 v25, 0xffff0000, v3
	v_fmac_f32_e32 v38, v25, v25
	v_fmac_f32_e32 v69, v25, v24
	s_waitcnt vmcnt(2)
; __device__ __forceinline__ float bf2f(bf16_t v) { return __uint_as_float(((unsigned)v) << 16); }
; __device__ __forceinline__ float xor32f(float x) { auto rr = __builtin_amdgcn_permlane32_swap(__float_as_uint(x), __float_as_uint(x), false, false); return __uint_as_float(rr[0]) + __uint_as_float(rr[1]); }
;     ...
;         for (int d0 = 0; d0 < 4; ++d0) {
; #pragma unroll
;             for (int j = 0; j < 8; ++j) { const float qv = bf2f((bf16_t)qr[d0][j]), kv = bf2f((bf16_t)kk[d0][j]); if (d0 < 2) { qa2 += qv * qv; dra += qv * kv; } else { qb2 += qv * qv; drb += qv * kv; } } }
;         qa2 = xor32f(qa2); qb2 = xor32f(qb2); dra = xor32f(dra); drb = xor32f(drb);
;         qa2 = max32f(qa2); qb2 = max32f(qb2);
;         if (lane == 0) { wsf[0] = qa2; wsf[1] = qb2; }
	v_lshlrev_b32_e32 v24, 16, v28
	v_lshlrev_b32_e32 v25, 16, v4
	v_fmac_f32_e32 v38, v25, v25
	v_fmac_f32_e32 v69, v25, v24
	v_and_b32_e32 v24, 0xffff0000, v28
	v_and_b32_e32 v25, 0xffff0000, v4
	v_fmac_f32_e32 v38, v25, v25
	v_fmac_f32_e32 v69, v25, v24
	v_lshlrev_b32_e32 v24, 16, v29
	v_lshlrev_b32_e32 v25, 16, v5
	v_fmac_f32_e32 v38, v25, v25
	v_fmac_f32_e32 v69, v25, v24
	v_and_b32_e32 v24, 0xffff0000, v29
	v_and_b32_e32 v25, 0xffff0000, v5
	v_fmac_f32_e32 v38, v25, v25
	v_fmac_f32_e32 v69, v25, v24
	v_lshlrev_b32_e32 v24, 16, v30
	v_lshlrev_b32_e32 v25, 16, v6
	v_fmac_f32_e32 v38, v25, v25
	v_fmac_f32_e32 v69, v25, v24
	v_and_b32_e32 v24, 0xffff0000, v30
	v_and_b32_e32 v25, 0xffff0000, v6
	v_fmac_f32_e32 v38, v25, v25
	v_fmac_f32_e32 v69, v25, v24
	v_lshlrev_b32_e32 v24, 16, v31
	v_lshlrev_b32_e32 v25, 16, v7
	v_fmac_f32_e32 v38, v25, v25
	v_fmac_f32_e32 v69, v25, v24
	v_and_b32_e32 v24, 0xffff0000, v31
	v_and_b32_e32 v25, 0xffff0000, v7
	v_fmac_f32_e32 v38, v25, v25
	v_fmac_f32_e32 v69, v25, v24
	s_waitcnt vmcnt(1)
	v_lshlrev_b32_e32 v24, 16, v32
	v_lshlrev_b32_e32 v25, 16, v8
	v_and_b32_e32 v26, 0xffff0000, v8
	v_fma_f32 v70, v25, v24, 0
	v_and_b32_e32 v24, 0xffff0000, v32
	v_mul_f32_e32 v27, v26, v26
	v_fmac_f32_e32 v27, v25, v25
	v_fmac_f32_e32 v70, v26, v24
	v_lshlrev_b32_e32 v24, 16, v33
	v_lshlrev_b32_e32 v25, 16, v9
	v_fmac_f32_e32 v27, v25, v25
	v_fmac_f32_e32 v70, v25, v24
	v_and_b32_e32 v24, 0xffff0000, v33
	v_and_b32_e32 v25, 0xffff0000, v9
	v_fmac_f32_e32 v27, v25, v25
	v_fmac_f32_e32 v70, v25, v24
	v_lshlrev_b32_e32 v24, 16, v34
	v_lshlrev_b32_e32 v25, 16, v10
	v_fmac_f32_e32 v27, v25, v25
	v_fmac_f32_e32 v70, v25, v24
	v_and_b32_e32 v24, 0xffff0000, v34
	v_and_b32_e32 v25, 0xffff0000, v10
	v_fmac_f32_e32 v27, v25, v25
	v_fmac_f32_e32 v70, v25, v24
	v_lshlrev_b32_e32 v24, 16, v35
	v_lshlrev_b32_e32 v25, 16, v11
	v_fmac_f32_e32 v27, v25, v25
	v_fmac_f32_e32 v70, v25, v24
	v_and_b32_e32 v24, 0xffff0000, v35
	v_and_b32_e32 v25, 0xffff0000, v11
	v_fmac_f32_e32 v27, v25, v25
	v_fmac_f32_e32 v70, v25, v24
	s_waitcnt vmcnt(0)
	v_lshlrev_b32_e32 v24, 16, v16
	v_lshlrev_b32_e32 v25, 16, v12
	v_fmac_f32_e32 v27, v25, v25
	v_fmac_f32_e32 v70, v25, v24
	v_and_b32_e32 v16, 0xffff0000, v16
	v_and_b32_e32 v24, 0xffff0000, v12
	v_fmac_f32_e32 v27, v24, v24
	v_fmac_f32_e32 v70, v24, v16
	v_lshlrev_b32_e32 v16, 16, v17
	v_lshlrev_b32_e32 v24, 16, v13
	v_fmac_f32_e32 v27, v24, v24
	v_fmac_f32_e32 v70, v24, v16
	v_and_b32_e32 v16, 0xffff0000, v17
	v_and_b32_e32 v17, 0xffff0000, v13
	v_fmac_f32_e32 v27, v17, v17
	v_fmac_f32_e32 v70, v17, v16
	v_lshlrev_b32_e32 v16, 16, v18
	v_lshlrev_b32_e32 v17, 16, v14
	v_fmac_f32_e32 v27, v17, v17
	v_fmac_f32_e32 v70, v17, v16
	v_and_b32_e32 v16, 0xffff0000, v18
	v_and_b32_e32 v17, 0xffff0000, v14
	v_fmac_f32_e32 v27, v17, v17
	v_fmac_f32_e32 v70, v17, v16
	v_lshlrev_b32_e32 v16, 16, v19
	v_lshlrev_b32_e32 v17, 16, v15
	v_fmac_f32_e32 v27, v17, v17
	v_fmac_f32_e32 v70, v17, v16
	v_and_b32_e32 v16, 0xffff0000, v15
	v_and_b32_e32 v17, 0xffff0000, v19
	v_fmac_f32_e32 v70, v16, v17
	v_fmac_f32_e32 v27, v16, v16
	v_mov_b32_e32 v16, v38
	s_nop 1
	v_permlane32_swap_b32_e32 v38, v16
	v_add_f32_e32 v16, v38, v16
	v_mov_b32_e32 v18, v16
	v_mov_b32_e32 v17, v27
	s_nop 1
	v_permlane32_swap_b32_e32 v27, v17
	v_mov_b32_dpp v18, v18 row_shr:1 row_mask:0xf bank_mask:0xf
	v_max_f32_e32 v18, v18, v18
	v_max_f32_e32 v16, v16, v18
	v_mov_b32_e32 v18, v16
	v_add_f32_e32 v17, v27, v17
	v_mov_b32_e32 v71, v69
	v_mov_b32_dpp v18, v18 row_shr:2 row_mask:0xf bank_mask:0xf
	v_max_f32_e32 v18, v18, v18
	v_max_f32_e32 v16, v16, v18
	v_mov_b32_e32 v18, v16
	v_mov_b32_e32 v72, v70
	v_permlane32_swap_b32_e32 v69, v71
	v_mov_b32_dpp v18, v18 row_shr:4 row_mask:0xf bank_mask:0xf
	v_max_f32_e32 v18, v18, v18
	v_max_f32_e32 v16, v16, v18
	v_mov_b32_e32 v18, v16
	v_permlane32_swap_b32_e32 v70, v72
	s_nop 0
	v_mov_b32_dpp v18, v18 row_shr:8 row_mask:0xf bank_mask:0xf
	v_max_f32_e32 v18, v18, v18
	v_max_f32_e32 v16, v16, v18
	s_nop 0
	v_readlane_b32 s22, v16, 15
	v_readlane_b32 s26, v16, 31
	v_mov_b32_e32 v16, v17
	s_nop 1
	v_mov_b32_dpp v16, v16 row_shr:1 row_mask:0xf bank_mask:0xf
	v_max_f32_e32 v16, v16, v16
	v_max_f32_e32 v16, v17, v16
	v_mov_b32_e32 v17, v16
	s_nop 1
	v_mov_b32_dpp v17, v17 row_shr:2 row_mask:0xf bank_mask:0xf
	v_max_f32_e32 v17, v17, v17
	v_max_f32_e32 v16, v16, v17
	v_mov_b32_e32 v17, v16
	s_nop 1
	v_mov_b32_dpp v17, v17 row_shr:4 row_mask:0xf bank_mask:0xf
	v_max_f32_e32 v17, v17, v17
	v_max_f32_e32 v16, v16, v17
	v_mov_b32_e32 v17, v16
	s_nop 1
	v_mov_b32_dpp v17, v17 row_shr:8 row_mask:0xf bank_mask:0xf
	v_max_f32_e32 v17, v17, v17
	v_max_f32_e32 v16, v16, v17
	s_nop 0
	v_readlane_b32 s27, v16, 15
	v_readlane_b32 s28, v16, 31
	s_and_saveexec_b64 s[36:37], vcc
	s_cbranch_execz .LBB0_312
	v_max_f32_e64 v16, s28, s28
	v_max_f32_e64 v17, s27, s27
	v_max_f32_e32 v17, v17, v16
	v_max_f32_e64 v16, s26, s26
	v_max_f32_e64 v18, s22, s22
	v_max_f32_e32 v16, v18, v16
	v_mov_b32_e32 v18, s20
	ds_write_b64 v18, v[16:17]
